# windowed GQA: skip the window-mask block on the two centre key tiles (always inside the window)
# baseline (speedup 1.0000x reference)
.LBB0_186:
	s_cmp_gt_u32 s12, 4
	s_cselect_b32 s0, s15, -1
	s_add_i32 s0, s0, s12
	s_cmp_lt_i32 s0, 4
	s_cbranch_scc1 .LBB0_190
	s_cmp_eq_u32 s0, 6
	s_cbranch_scc1 .LBB0_190
	s_cmp_eq_u32 s0, 7
	s_cbranch_scc1 .LBB0_190
	v_lshl_add_u32 v102, s0, 6, v122
	v_add_u32_e32 v112, 0xffffff1f, v102
	v_cmp_lt_u32_e64 s[0:1], s4, v112
	v_add_u32_e32 v112, 0xffffff00, v102
	v_cmp_lt_u32_e64 s[38:39], s4, v112
	v_add_u32_e32 v112, 0xffffff20, v102
	v_cndmask_b32_e64 v34, v233, v34, s[0:1]
	v_cmp_lt_u32_e64 s[0:1], s4, v112
	v_add_u32_e32 v112, 0xffffff01, v102
	v_cmp_lt_u32_e64 s[40:41], s4, v112
	v_add_u32_e32 v112, 0xffffff21, v102
	v_cndmask_b32_e64 v35, v233, v35, s[0:1]
	v_cmp_lt_u32_e64 s[0:1], s4, v112
	v_add_u32_e32 v112, 0xffffff02, v102
	v_cmp_lt_u32_e64 s[42:43], s4, v112
	v_add_u32_e32 v112, 0xffffff22, v102
	v_cndmask_b32_e64 v36, v233, v36, s[0:1]
	v_cmp_lt_u32_e64 s[0:1], s4, v112
	v_add_u32_e32 v112, 0xffffff07, v102
	v_cmp_lt_u32_e64 s[44:45], s4, v112
	v_add_u32_e32 v112, 0xffffff27, v102
	v_cndmask_b32_e64 v37, v233, v37, s[0:1]
	v_cmp_lt_u32_e64 s[0:1], s4, v112
	v_add_u32_e32 v112, 0xffffff08, v102
	v_cmp_lt_u32_e64 s[46:47], s4, v112
	v_add_u32_e32 v112, 0xffffff28, v102
	v_cndmask_b32_e64 v38, v233, v38, s[0:1]
	v_cmp_lt_u32_e64 s[0:1], s4, v112
	v_add_u32_e32 v112, 0xffffff09, v102
	v_cmp_lt_u32_e64 s[48:49], s4, v112
	v_add_u32_e32 v112, 0xffffff29, v102
	v_cndmask_b32_e64 v39, v233, v39, s[0:1]
	v_cmp_lt_u32_e64 s[0:1], s4, v112
	v_add_u32_e32 v112, 0xffffff0a, v102
	v_cmp_lt_u32_e64 s[50:51], s4, v112
	v_add_u32_e32 v112, 0xffffff2a, v102
	v_cndmask_b32_e64 v40, v233, v40, s[0:1]
	v_cmp_lt_u32_e64 s[0:1], s4, v112
	v_add_u32_e32 v112, 0xffffff0f, v102
	v_cmp_lt_u32_e64 s[52:53], s4, v112
	v_add_u32_e32 v112, 0xffffff2f, v102
	v_cndmask_b32_e64 v41, v233, v41, s[0:1]
	v_cmp_lt_u32_e64 s[0:1], s4, v112
	v_add_u32_e32 v112, 0xffffff10, v102
	v_cmp_lt_u32_e64 s[54:55], s4, v112
	v_add_u32_e32 v112, 0xffffff30, v102
	v_cndmask_b32_e64 v42, v233, v42, s[0:1]
	v_cmp_lt_u32_e64 s[0:1], s4, v112
	v_add_u32_e32 v112, 0xffffff11, v102
	v_cmp_lt_u32_e64 s[56:57], s4, v112
	v_add_u32_e32 v112, 0xffffff31, v102
	v_cndmask_b32_e64 v43, v233, v43, s[0:1]
	v_cmp_lt_u32_e64 s[0:1], s4, v112
	v_add_u32_e32 v112, 0xffffff12, v102
	v_cmp_gt_u32_e32 vcc, s20, v102
	v_cndmask_b32_e64 v44, v233, v44, s[0:1]
	v_cmp_lt_u32_e64 s[0:1], s4, v112
	v_add_u32_e32 v112, 0xffffff32, v102
	v_cmp_lt_u32_e64 s[60:61], s4, v112
	v_add_u32_e32 v112, 0xffffff17, v102
	s_nop 0
	v_cndmask_b32_e64 v45, v233, v45, s[60:61]
	v_cmp_lt_u32_e64 s[60:61], s4, v112
	v_add_u32_e32 v112, 0xffffff37, v102
	v_cmp_lt_u32_e64 s[62:63], s4, v112
	v_add_u32_e32 v112, 0xffffff18, v102
	s_nop 0
	v_cndmask_b32_e64 v46, v233, v46, s[62:63]
	v_cmp_lt_u32_e64 s[62:63], s4, v112
	v_add_u32_e32 v112, 0xffffff38, v102
	v_cmp_lt_u32_e64 s[64:65], s4, v112
	v_add_u32_e32 v112, 0xffffff19, v102
	s_nop 0
	v_cndmask_b32_e64 v47, v233, v47, s[64:65]
	v_cmp_lt_u32_e64 s[64:65], s4, v112
	v_add_u32_e32 v112, 0xffffff39, v102
	v_cmp_lt_u32_e64 s[66:67], s4, v112
	v_add_u32_e32 v112, 0xffffff1a, v102
	v_add_u32_e32 v102, 0xffffff3a, v102
	v_cndmask_b32_e64 v48, v233, v48, s[66:67]
	v_cmp_lt_u32_e64 s[66:67], s4, v112
	v_cmp_gt_u32_e64 s[70:71], s23, v102
	s_and_saveexec_b64 s[8:9], s[70:71]
	v_mov_b32_e32 v49, s21
	s_or_b64 exec, exec, s[8:9]
	v_cndmask_b32_e32 v50, v233, v50, vcc
	v_cndmask_b32_e64 v51, v233, v51, s[38:39]
	v_cndmask_b32_e64 v52, v233, v52, s[40:41]
	v_cndmask_b32_e64 v53, v233, v53, s[42:43]
	v_cndmask_b32_e64 v54, v233, v54, s[44:45]
	v_cndmask_b32_e64 v55, v233, v55, s[46:47]
	v_cndmask_b32_e64 v56, v233, v56, s[48:49]
	v_cndmask_b32_e64 v57, v233, v57, s[50:51]
	v_cndmask_b32_e64 v58, v233, v58, s[52:53]
	v_cndmask_b32_e64 v59, v233, v59, s[54:55]
	v_cndmask_b32_e64 v60, v233, v60, s[56:57]
	v_cndmask_b32_e64 v61, v233, v61, s[0:1]
	v_cndmask_b32_e64 v62, v233, v62, s[60:61]
	v_cndmask_b32_e64 v63, v233, v63, s[62:63]
	v_cndmask_b32_e64 v64, v233, v64, s[64:65]
	v_cndmask_b32_e64 v65, v233, v65, s[66:67]
	v_readlane_b32 s70, v255, 15
	v_readlane_b32 s71, v255, 16

.LBB0_207:
	s_cmp_gt_u32 s15, 3
	s_cselect_b32 s0, s12, 0
	s_and_b32 s19, s15, 1
	s_mul_i32 s1, s19, 0x3400
	v_add_u32_e32 v95, s1, v121
	ds_read_b128 v[124:127], v95
	ds_read_b128 v[128:131], v95 offset:32
	ds_read_b128 v[132:135], v95 offset:4608
	ds_read_b128 v[136:139], v95 offset:64
	ds_read_b128 v[140:143], v95 offset:4640
	ds_read_b128 v[144:147], v95 offset:4672
	s_add_i32 s10, s15, 1
	s_and_b32 s22, s10, 1
	v_xor_b32_e32 v32, 0x80000000, v65
	s_add_i32 s0, s0, s15
	s_mul_i32 s1, s22, 0x2400
	v_mov_b32_e32 v33, v32
	v_mov_b32_e32 v34, v32
	v_mov_b32_e32 v35, v32
	v_mov_b32_e32 v36, v32
	v_mov_b32_e32 v37, v32
	v_mov_b32_e32 v38, v32
	v_mov_b32_e32 v39, v32
	v_mov_b32_e32 v40, v32
	v_mov_b32_e32 v41, v32
	v_mov_b32_e32 v42, v32
	v_mov_b32_e32 v43, v32
	v_mov_b32_e32 v44, v32
	v_mov_b32_e32 v45, v32
	v_mov_b32_e32 v46, v32
	v_mov_b32_e32 v47, v32
	v_add_u32_e32 v96, s1, v118
	s_waitcnt lgkmcnt(5)
	v_mfma_f32_32x32x16_bf16 v[48:63], v[124:127], v[66:69], v[32:47]
	s_waitcnt lgkmcnt(3)
	v_mfma_f32_32x32x16_bf16 v[32:47], v[132:135], v[66:69], v[32:47]
	ds_read_b128 v[124:127], v95 offset:96
	ds_read_b128 v[132:135], v95 offset:4704
	v_mfma_f32_32x32x16_bf16 v[48:63], v[128:131], v[70:73], v[48:63]
	s_waitcnt lgkmcnt(3)
	v_mfma_f32_32x32x16_bf16 v[32:47], v[140:143], v[70:73], v[32:47]
	ds_read_b64_tr_b16 v[128:129], v96 offset:26624
	ds_read_b64_tr_b16 v[130:131], v96 offset:27776
	ds_read_b64_tr_b16 v[142:143], v96 offset:27840
	ds_read_b64_tr_b16 v[140:141], v96 offset:26688
	v_mfma_f32_32x32x16_bf16 v[48:63], v[136:139], v[74:77], v[48:63]
	s_waitcnt lgkmcnt(6)
	v_mfma_f32_32x32x16_bf16 v[32:47], v[144:147], v[74:77], v[32:47]
	ds_read_b64_tr_b16 v[136:137], v96 offset:28928
	ds_read_b64_tr_b16 v[138:139], v96 offset:30080
	ds_read_b64_tr_b16 v[146:147], v96 offset:30144
	ds_read_b64_tr_b16 v[144:145], v96 offset:28992
	s_waitcnt lgkmcnt(9)
	v_mfma_f32_32x32x16_bf16 v[48:63], v[124:127], v[78:81], v[48:63]
	s_waitcnt lgkmcnt(8)
	v_mfma_f32_32x32x16_bf16 v[32:47], v[132:135], v[78:81], v[32:47]
	ds_read_b64_tr_b16 v[124:125], v96 offset:31232
	ds_read_b64_tr_b16 v[126:127], v96 offset:32384
	ds_read_b64_tr_b16 v[134:135], v96 offset:32448
	ds_read_b64_tr_b16 v[132:133], v96 offset:31296
	s_waitcnt lgkmcnt(10)
	v_mfma_f32_32x32x16_bf16 v[16:31], v[128:131], v[112:115], v[16:31]
	s_waitcnt lgkmcnt(8)
	v_mfma_f32_32x32x16_bf16 v[0:15], v[140:143], v[112:115], v[0:15]
	ds_read_b64_tr_b16 v[112:113], v96 offset:33536
	ds_read_b64_tr_b16 v[114:115], v96 offset:34688
	ds_read_b64_tr_b16 v[130:131], v96 offset:34752
	ds_read_b64_tr_b16 v[128:129], v96 offset:33600
	s_waitcnt lgkmcnt(10)
	v_mfma_f32_32x32x16_bf16 v[16:31], v[136:139], v[108:111], v[16:31]
	s_waitcnt lgkmcnt(8)
	v_mfma_f32_32x32x16_bf16 v[0:15], v[144:147], v[108:111], v[0:15]
	s_waitcnt lgkmcnt(6)
	v_mfma_f32_32x32x16_bf16 v[16:31], v[124:127], v[104:107], v[16:31]
	s_waitcnt lgkmcnt(4)
	v_mfma_f32_32x32x16_bf16 v[0:15], v[132:135], v[104:107], v[0:15]
	s_waitcnt lgkmcnt(2)
	v_mfma_f32_32x32x16_bf16 v[16:31], v[112:115], v[100:103], v[16:31]
	s_waitcnt lgkmcnt(0)
	v_mfma_f32_32x32x16_bf16 v[0:15], v[128:131], v[100:103], v[0:15]
	s_cmp_lt_i32 s0, 4
	s_cbranch_scc1 .LBB0_211
	s_cmp_eq_u32 s0, 6
	s_cbranch_scc1 .LBB0_211
	s_cmp_eq_u32 s0, 7
	s_cbranch_scc1 .LBB0_211
	v_lshl_add_u32 v95, s0, 6, v122
	v_add_u32_e32 v96, 0xffffff1f, v95
	v_cmp_lt_u32_e64 s[0:1], s4, v96
	v_add_u32_e32 v96, 0xffffff00, v95
	v_cmp_lt_u32_e64 s[38:39], s4, v96
	v_add_u32_e32 v96, 0xffffff20, v95
	v_cndmask_b32_e64 v32, v233, v32, s[0:1]
	v_cmp_lt_u32_e64 s[0:1], s4, v96
	v_add_u32_e32 v96, 0xffffff01, v95
	v_cmp_lt_u32_e64 s[40:41], s4, v96
	v_add_u32_e32 v96, 0xffffff21, v95
	v_cndmask_b32_e64 v33, v233, v33, s[0:1]
	v_cmp_lt_u32_e64 s[0:1], s4, v96
	v_add_u32_e32 v96, 0xffffff02, v95
	v_cmp_lt_u32_e64 s[42:43], s4, v96
	v_add_u32_e32 v96, 0xffffff22, v95
	v_cndmask_b32_e64 v34, v233, v34, s[0:1]
	v_cmp_lt_u32_e64 s[0:1], s4, v96
	v_add_u32_e32 v96, 0xffffff07, v95
	v_cmp_lt_u32_e64 s[44:45], s4, v96
	v_add_u32_e32 v96, 0xffffff27, v95
	v_cndmask_b32_e64 v35, v233, v35, s[0:1]
	v_cmp_lt_u32_e64 s[0:1], s4, v96
	v_add_u32_e32 v96, 0xffffff08, v95
	v_cmp_lt_u32_e64 s[46:47], s4, v96
	v_add_u32_e32 v96, 0xffffff28, v95
	v_cndmask_b32_e64 v36, v233, v36, s[0:1]
	v_cmp_lt_u32_e64 s[0:1], s4, v96
	v_add_u32_e32 v96, 0xffffff09, v95
	v_cmp_lt_u32_e64 s[48:49], s4, v96
	v_add_u32_e32 v96, 0xffffff29, v95
	v_cndmask_b32_e64 v37, v233, v37, s[0:1]
	v_cmp_lt_u32_e64 s[0:1], s4, v96
	v_add_u32_e32 v96, 0xffffff0a, v95
	v_cmp_lt_u32_e64 s[50:51], s4, v96
	v_add_u32_e32 v96, 0xffffff2a, v95
	v_cndmask_b32_e64 v38, v233, v38, s[0:1]
	v_cmp_lt_u32_e64 s[0:1], s4, v96
	v_add_u32_e32 v96, 0xffffff0f, v95
	v_cmp_lt_u32_e64 s[52:53], s4, v96
	v_add_u32_e32 v96, 0xffffff2f, v95
	v_cndmask_b32_e64 v39, v233, v39, s[0:1]
	v_cmp_lt_u32_e64 s[0:1], s4, v96
	v_add_u32_e32 v96, 0xffffff10, v95
	v_cmp_lt_u32_e64 s[54:55], s4, v96
	v_add_u32_e32 v96, 0xffffff30, v95
	v_cndmask_b32_e64 v40, v233, v40, s[0:1]
	v_cmp_lt_u32_e64 s[0:1], s4, v96
	v_add_u32_e32 v96, 0xffffff11, v95
	v_cmp_lt_u32_e64 s[56:57], s4, v96
	v_add_u32_e32 v96, 0xffffff31, v95
	v_cndmask_b32_e64 v41, v233, v41, s[0:1]
	v_cmp_lt_u32_e64 s[0:1], s4, v96
	v_add_u32_e32 v96, 0xffffff12, v95
	v_cmp_gt_u32_e32 vcc, s20, v95
	v_cndmask_b32_e64 v42, v233, v42, s[0:1]
	v_cmp_lt_u32_e64 s[0:1], s4, v96
	v_add_u32_e32 v96, 0xffffff32, v95
	v_cmp_lt_u32_e64 s[60:61], s4, v96
	v_add_u32_e32 v96, 0xffffff17, v95
	s_nop 0
	v_cndmask_b32_e64 v43, v233, v43, s[60:61]
	v_cmp_lt_u32_e64 s[60:61], s4, v96
	v_add_u32_e32 v96, 0xffffff37, v95
	v_cmp_lt_u32_e64 s[62:63], s4, v96
	v_add_u32_e32 v96, 0xffffff18, v95
	s_nop 0
	v_cndmask_b32_e64 v44, v233, v44, s[62:63]
	v_cmp_lt_u32_e64 s[62:63], s4, v96
	v_add_u32_e32 v96, 0xffffff38, v95
	v_cmp_lt_u32_e64 s[64:65], s4, v96
	v_add_u32_e32 v96, 0xffffff19, v95
	s_nop 0
	v_cndmask_b32_e64 v45, v233, v45, s[64:65]
	v_cmp_lt_u32_e64 s[64:65], s4, v96
	v_add_u32_e32 v96, 0xffffff39, v95
	v_cmp_lt_u32_e64 s[66:67], s4, v96
	v_add_u32_e32 v96, 0xffffff1a, v95
	v_add_u32_e32 v95, 0xffffff3a, v95
	v_cndmask_b32_e64 v46, v233, v46, s[66:67]
	v_cmp_lt_u32_e64 s[66:67], s4, v96
	v_cmp_gt_u32_e64 s[70:71], s23, v95
	s_and_saveexec_b64 s[8:9], s[70:71]
	v_mov_b32_e32 v47, s21
	s_or_b64 exec, exec, s[8:9]
	v_cndmask_b32_e32 v48, v233, v48, vcc
	v_cndmask_b32_e64 v49, v233, v49, s[38:39]
	v_cndmask_b32_e64 v50, v233, v50, s[40:41]
	v_cndmask_b32_e64 v51, v233, v51, s[42:43]
	v_cndmask_b32_e64 v52, v233, v52, s[44:45]
	v_cndmask_b32_e64 v53, v233, v53, s[46:47]
	v_cndmask_b32_e64 v54, v233, v54, s[48:49]
	v_cndmask_b32_e64 v55, v233, v55, s[50:51]
	v_cndmask_b32_e64 v56, v233, v56, s[52:53]
	v_cndmask_b32_e64 v57, v233, v57, s[54:55]
	v_cndmask_b32_e64 v58, v233, v58, s[56:57]
	v_cndmask_b32_e64 v59, v233, v59, s[0:1]
	v_cndmask_b32_e64 v60, v233, v60, s[60:61]
	v_cndmask_b32_e64 v61, v233, v61, s[62:63]
	v_cndmask_b32_e64 v62, v233, v62, s[64:65]
	v_cndmask_b32_e64 v63, v233, v63, s[66:67]
	v_readlane_b32 s70, v255, 15
	v_readlane_b32 s71, v255, 16
